# EpiQKV rope-table loads software-pipelined one step ahead (no wait on the previous step stores); norm-gain waits counted down
# speedup vs baseline: 1.0183x; 1.0001x over previous
; __device__ __forceinline__ u32x4 pack8(const f32x4 a, const f32x4 b) { u32x4 w; w.x = pk2(a[0], a[1]); w.y = pk2(a[2], a[3]); w.z = pk2(b[0], b[1]); w.w = pk2(b[2], b[3]); return w; }
;     __device__ __forceinline__ void operator()(const f32x4 (&acc)[2][2][4][2], const Unit& u, int wr, int wc, int fr_, int fq_) const {
;     ...
;             for (int m = 0; m < 4; ++m) { const int rl = ai * HALF + wr * 64 + m * 16 + fr;
;                 f32x4 a0 = acc[ai][0][m][0], a1 = acc[ai][0][m][1], b0 = acc[ai][1][m][0], b1 = acc[ai][1][m][1];
;                 if (norm_on) { float ss = 0.f;
; #pragma unroll
;                     for (int e = 0; e < 4; ++e) ss += a0[e] * a0[e] + a1[e] * a1[e] + b0[e] * b0[e] + b1[e] * b1[e];
;                     ss += __shfl_xor(ss, 16); ss += __shfl_xor(ss, 32);
;                     const float ri = rsqrtf(ss * (1.0f / 64.0f) + 1e-6f);
;                     a0 = a0 * ri * g0[0]; a1 = a1 * ri * g1[0]; b0 = b0 * ri * g0[1]; b1 = b1 * ri * g1[1]; }
;                 if (rope_on) { const float* cp = rope + (size_t)(t0 + rl) * 32 + 8 * fq; const float* sp = cp + 2048 * 32;
;                     const f32x4 c0 = *(const f32x4*)cp, c1 = *(const f32x4*)(cp + 4), s0 = *(const f32x4*)sp, s1 = *(const f32x4*)(sp + 4);
;                     const f32x4 na0 = a0 * c0 - b0 * s0, nb0 = a0 * s0 + b0 * c0, na1 = a1 * c1 - b1 * s1, nb1 = a1 * s1 + b1 * c1;
;                     a0 = na0; b0 = nb0; a1 = na1; b1 = nb1; }
;                 a0 = a0 * qs; a1 = a1 * qs; b0 = b0 * qs; b1 = b1 * qs;
;                 bf16_t* rowp = dst + (rowbase + rl) * ld + colh;
;                 *(u32x4*)(rowp) = pack8(a0, a1); *(u32x4*)(rowp + 32) = pack8(b0, b1); }
.LBB0_195:
	s_lshl_b32 s10, s10, 8
	s_and_b32 s35, s10, 0x700
	s_and_b64 s[10:11], s[42:43], s[62:63]
	s_cmpk_lt_i32 s60, 0x80
	s_cselect_b64 s[60:61], -1, 0
	s_and_b64 s[60:61], s[10:11], s[60:61]
	v_cndmask_b32_e64 v157, 0, 1, s[60:61]
	v_cmp_ne_u32_e64 s[10:11], 1, v157
	s_andn2_b64 vcc, exec, s[60:61]
	v_add_u32_e32 v158, s1, v156
	s_cbranch_vccnz .LBB0_197
	v_add_u32_e32 v156, s35, v158
	v_ashrrev_i32_e32 v157, 31, v156
	v_lshlrev_b64 v[156:157], 7, v[156:157]
	v_lshl_add_u64 v[156:157], s[28:29], 0, v[156:157]
	v_lshl_add_u64 v[156:157], v[154:155], 2, v[156:157]
	v_lshl_add_u64 v[176:177], v[156:157], 0, s[88:89]
	v_mov_b64_e32 v[238:239], v[156:157]
	global_load_dwordx4 v[164:167], v[156:157], off offset:16
	global_load_dwordx4 v[168:171], v[156:157], off
	v_add_co_u32_e32 v156, vcc, 0x40000, v156
	s_nop 1
	v_addc_co_u32_e32 v157, vcc, 0, v157, vcc
	global_load_dwordx4 v[172:175], v[156:157], off
	s_nop 0
	global_load_dwordx4 v[176:179], v[176:177], off offset:16
	s_waitcnt vmcnt(0)
	s_mov_b64 s[100:101], 0x800
	v_lshl_add_u64 v[240:241], v[238:239], 0, s[100:101]
	v_lshl_add_u64 v[242:243], v[240:241], 0, s[88:89]
	global_load_dwordx4 v[184:187], v[240:241], off offset:16
	global_load_dwordx4 v[194:197], v[240:241], off
	global_load_dwordx4 v[230:233], v[242:243], off
	global_load_dwordx4 v[234:237], v[242:243], off offset:16
	v_pk_mul_f32 v[180:181], v[132:133], v[172:173]
	v_pk_mul_f32 v[156:157], v[134:135], v[174:175]
	v_pk_fma_f32 v[180:181], v[140:141], v[168:169], v[180:181] neg_lo:[0,0,1] neg_hi:[0,0,1]
	v_pk_mul_f32 v[140:141], v[140:141], v[172:173]
	v_pk_fma_f32 v[182:183], v[142:143], v[170:171], v[156:157] neg_lo:[0,0,1] neg_hi:[0,0,1]
	v_pk_mul_f32 v[142:143], v[142:143], v[174:175]
	v_pk_fma_f32 v[132:133], v[132:133], v[168:169], v[140:141]
	v_pk_mul_f32 v[140:141], v[130:131], v[178:179]
	v_pk_mul_f32 v[156:157], v[128:129], v[176:177]
	v_pk_fma_f32 v[134:135], v[134:135], v[170:171], v[142:143]
	v_pk_fma_f32 v[142:143], v[138:139], v[166:167], v[140:141] neg_lo:[0,0,1] neg_hi:[0,0,1]
	v_pk_fma_f32 v[140:141], v[136:137], v[164:165], v[156:157] neg_lo:[0,0,1] neg_hi:[0,0,1]
	v_pk_mul_f32 v[138:139], v[138:139], v[178:179]
	v_pk_mul_f32 v[136:137], v[136:137], v[176:177]
	v_pk_fma_f32 v[130:131], v[130:131], v[166:167], v[138:139]
	v_pk_fma_f32 v[128:129], v[128:129], v[164:165], v[136:137]
	v_mov_b64_e32 v[136:137], v[140:141]
	v_mov_b64_e32 v[138:139], v[142:143]
	v_mov_b64_e32 v[140:141], v[180:181]
	v_mov_b64_e32 v[142:143], v[182:183]
.LBB0_197:
	s_lshl_b32 s37, s56, 8
	s_or_b32 s37, s37, s91
	v_add_u32_e32 v156, s37, v154
	s_add_u32 s58, s24, s58
	v_ashrrev_i32_e32 v159, 31, v158
	s_addc_u32 s59, s25, s59
	v_ashrrev_i32_e32 v157, 31, v156
	v_pk_mul_f32 v[166:167], s[54:55], v[128:129] op_sel_hi:[0,1]
	v_lshl_add_u64 v[128:129], s[50:51], 0, v[158:159]
	v_lshl_add_u64 v[156:157], v[156:157], 1, s[58:59]
	v_pk_mul_f32 v[164:165], s[54:55], v[130:131] op_sel_hi:[0,1]
	v_mad_u64_u32 v[130:131], s[58:59], v128, s52, 0
	v_mov_b32_e32 v128, v131
	v_mad_u64_u32 v[128:129], s[58:59], v129, s52, v[128:129]
	v_pk_mul_f32 v[142:143], s[54:55], v[142:143] op_sel_hi:[0,1]
	v_pk_mul_f32 v[140:141], s[54:55], v[140:141] op_sel_hi:[0,1]
	v_pk_mul_f32 v[138:139], s[54:55], v[138:139] op_sel_hi:[0,1]
	v_pk_mul_f32 v[136:137], s[54:55], v[136:137] op_sel_hi:[0,1]
	v_mov_b32_e32 v131, v128
	v_pk_mul_f32 v[134:135], s[54:55], v[134:135] op_sel_hi:[0,1]
	v_pk_mul_f32 v[132:133], s[54:55], v[132:133] op_sel_hi:[0,1]
	v_lshl_add_u64 v[168:169], v[130:131], 1, v[156:157]
	v_cvt_pk_bf16_f32 v128, v140, v141
	v_cvt_pk_bf16_f32 v129, v142, v143
	v_cvt_pk_bf16_f32 v130, v136, v137
	v_cvt_pk_bf16_f32 v131, v138, v139
	s_mov_b64 s[60:61], 0x600000
	global_store_dwordx4 v[168:169], v[128:131], off
	s_and_b64 vcc, exec, s[8:9]
	s_nop 0
	v_cvt_pk_bf16_f32 v128, v132, v133
	v_cvt_pk_bf16_f32 v129, v134, v135
	v_cvt_pk_bf16_f32 v130, v166, v167
	v_cvt_pk_bf16_f32 v131, v164, v165
	global_store_dwordx4 v[168:169], v[128:131], off offset:64
	s_cbranch_vccnz .LBB0_199
	s_nop 0
	v_pk_mul_f32 v[130:131], v[120:121], v[120:121]
	v_pk_mul_f32 v[128:129], v[122:123], v[122:123]
	v_pk_fma_f32 v[130:131], v[124:125], v[124:125], v[130:131]
	v_pk_fma_f32 v[128:129], v[126:127], v[126:127], v[128:129]
	v_pk_fma_f32 v[130:131], v[116:117], v[116:117], v[130:131]
	v_pk_fma_f32 v[128:129], v[118:119], v[118:119], v[128:129]
	v_pk_fma_f32 v[130:131], v[112:113], v[112:113], v[130:131]
	v_pk_fma_f32 v[128:129], v[114:115], v[114:115], v[128:129]
	v_add_f32_e32 v130, v130, v131
	v_add_f32_e32 v128, v128, v130
	v_cmp_lt_i32_e32 vcc, v206, v204
	v_add_f32_e32 v128, v129, v128
	s_nop 0
	v_cndmask_b32_e32 v129, v203, v206, vcc
	v_lshlrev_b32_e32 v129, 2, v129
	ds_bpermute_b32 v129, v129, v128
	v_cmp_lt_i32_e32 vcc, v205, v204
	s_waitcnt lgkmcnt(0)
	v_add_f32_e32 v128, v128, v129
	v_cndmask_b32_e32 v129, v203, v205, vcc
	v_lshlrev_b32_e32 v129, 2, v129
	ds_bpermute_b32 v129, v129, v128
	s_waitcnt lgkmcnt(0)
	v_add_f32_e32 v128, v128, v129
	v_fmamk_f32 v128, v128, 0x3c800000, v199
	v_mul_f32_e32 v129, 0x4b800000, v128
	v_cmp_gt_f32_e32 vcc, s64, v128
	s_nop 1
	v_cndmask_b32_e32 v128, v128, v129, vcc
	v_rsq_f32_e32 v128, v128
	s_nop 0
	v_mul_f32_e32 v129, 0x45800000, v128
	v_cndmask_b32_e32 v128, v128, v129, vcc
	v_pk_mul_f32 v[124:125], v[124:125], v[128:129] op_sel_hi:[1,0]
	v_pk_mul_f32 v[126:127], v[126:127], v[128:129] op_sel_hi:[1,0]
	v_pk_mul_f32 v[120:121], v[120:121], v[128:129] op_sel_hi:[1,0]
	v_pk_mul_f32 v[122:123], v[122:123], v[128:129] op_sel_hi:[1,0]
	v_pk_mul_f32 v[116:117], v[116:117], v[128:129] op_sel_hi:[1,0]
	v_pk_mul_f32 v[118:119], v[118:119], v[128:129] op_sel_hi:[1,0]
	v_pk_mul_f32 v[112:113], v[112:113], v[128:129] op_sel_hi:[1,0]
	v_pk_mul_f32 v[114:115], v[114:115], v[128:129] op_sel_hi:[1,0]
	s_waitcnt vmcnt(6)
	v_pk_mul_f32 v[126:127], v[78:79], v[126:127]
	v_pk_mul_f32 v[124:125], v[76:77], v[124:125]
	v_pk_mul_f32 v[122:123], v[70:71], v[122:123]
	v_pk_mul_f32 v[120:121], v[68:69], v[120:121]
	v_pk_mul_f32 v[118:119], v[74:75], v[118:119]
	v_pk_mul_f32 v[116:117], v[72:73], v[116:117]
	v_pk_mul_f32 v[114:115], v[66:67], v[114:115]
	v_pk_mul_f32 v[112:113], v[64:65], v[112:113]
; __device__ __forceinline__ u32x4 pack8(const f32x4 a, const f32x4 b) { u32x4 w; w.x = pk2(a[0], a[1]); w.y = pk2(a[2], a[3]); w.z = pk2(b[0], b[1]); w.w = pk2(b[2], b[3]); return w; }
;     __device__ __forceinline__ void operator()(const f32x4 (&acc)[2][2][4][2], const Unit& u, int wr, int wc, int fr_, int fq_) const {
;     ...
;             for (int m = 0; m < 4; ++m) { const int rl = ai * HALF + wr * 64 + m * 16 + fr;
;                 f32x4 a0 = acc[ai][0][m][0], a1 = acc[ai][0][m][1], b0 = acc[ai][1][m][0], b1 = acc[ai][1][m][1];
;                 if (norm_on) { float ss = 0.f;
; #pragma unroll
;                     for (int e = 0; e < 4; ++e) ss += a0[e] * a0[e] + a1[e] * a1[e] + b0[e] * b0[e] + b1[e] * b1[e];
;                     ss += __shfl_xor(ss, 16); ss += __shfl_xor(ss, 32);
;                     const float ri = rsqrtf(ss * (1.0f / 64.0f) + 1e-6f);
;                     a0 = a0 * ri * g0[0]; a1 = a1 * ri * g1[0]; b0 = b0 * ri * g0[1]; b1 = b1 * ri * g1[1]; }
;                 if (rope_on) { const float* cp = rope + (size_t)(t0 + rl) * 32 + 8 * fq; const float* sp = cp + 2048 * 32;
;                     const f32x4 c0 = *(const f32x4*)cp, c1 = *(const f32x4*)(cp + 4), s0 = *(const f32x4*)sp, s1 = *(const f32x4*)(sp + 4);
;                     const f32x4 na0 = a0 * c0 - b0 * s0, nb0 = a0 * s0 + b0 * c0, na1 = a1 * c1 - b1 * s1, nb1 = a1 * s1 + b1 * c1;
;                     a0 = na0; b0 = nb0; a1 = na1; b1 = nb1; }
;                 a0 = a0 * qs; a1 = a1 * qs; b0 = b0 * qs; b1 = b1 * qs;
;                 bf16_t* rowp = dst + (rowbase + rl) * ld + colh;
;                 *(u32x4*)(rowp) = pack8(a0, a1); *(u32x4*)(rowp + 32) = pack8(b0, b1); }
.LBB0_199:
	s_and_b64 vcc, exec, s[10:11]
	v_add_u32_e32 v128, 16, v158
	s_cbranch_vccnz .LBB0_201
	s_waitcnt vmcnt(2)
	v_mov_b64_e32 v[130:131], v[184:185]
	v_mov_b64_e32 v[132:133], v[186:187]
	v_mov_b64_e32 v[134:135], v[194:195]
	v_mov_b64_e32 v[136:137], v[196:197]
	v_mov_b64_e32 v[138:139], v[230:231]
	v_mov_b64_e32 v[140:141], v[232:233]
	v_mov_b64_e32 v[164:165], v[234:235]
	v_mov_b64_e32 v[166:167], v[236:237]
	s_mov_b64 s[100:101], 0x1000
	v_lshl_add_u64 v[240:241], v[238:239], 0, s[100:101]
	v_lshl_add_u64 v[242:243], v[240:241], 0, s[88:89]
	global_load_dwordx4 v[184:187], v[240:241], off offset:16
	global_load_dwordx4 v[194:197], v[240:241], off
	global_load_dwordx4 v[230:233], v[242:243], off
	global_load_dwordx4 v[234:237], v[242:243], off offset:16
	v_pk_mul_f32 v[168:169], v[116:117], v[138:139]
	v_pk_mul_f32 v[142:143], v[118:119], v[140:141]
	v_pk_fma_f32 v[168:169], v[124:125], v[134:135], v[168:169] neg_lo:[0,0,1] neg_hi:[0,0,1]
	v_pk_mul_f32 v[124:125], v[124:125], v[138:139]
	v_pk_fma_f32 v[170:171], v[126:127], v[136:137], v[142:143] neg_lo:[0,0,1] neg_hi:[0,0,1]
	v_pk_mul_f32 v[126:127], v[126:127], v[140:141]
	v_pk_fma_f32 v[116:117], v[116:117], v[134:135], v[124:125]
	v_pk_mul_f32 v[124:125], v[114:115], v[166:167]
	v_pk_mul_f32 v[134:135], v[112:113], v[164:165]
	v_pk_fma_f32 v[118:119], v[118:119], v[136:137], v[126:127]
	v_pk_fma_f32 v[126:127], v[122:123], v[132:133], v[124:125] neg_lo:[0,0,1] neg_hi:[0,0,1]
	v_pk_fma_f32 v[124:125], v[120:121], v[130:131], v[134:135] neg_lo:[0,0,1] neg_hi:[0,0,1]
	v_pk_mul_f32 v[122:123], v[122:123], v[166:167]
	v_pk_mul_f32 v[120:121], v[120:121], v[164:165]
	v_pk_fma_f32 v[114:115], v[114:115], v[132:133], v[122:123]
	v_pk_fma_f32 v[112:113], v[112:113], v[130:131], v[120:121]
	v_mov_b64_e32 v[120:121], v[124:125]
	v_mov_b64_e32 v[122:123], v[126:127]
	v_mov_b64_e32 v[124:125], v[168:169]
	v_mov_b64_e32 v[126:127], v[170:171]
.LBB0_201:
	s_mov_b32 s55, s54
	v_ashrrev_i32_e32 v129, 31, v128
	s_mov_b32 s58, s54
	s_mov_b32 s59, s54
	v_pk_mul_f32 v[132:133], s[54:55], v[112:113]
	v_lshl_add_u64 v[112:113], s[50:51], 0, v[128:129]
	v_pk_mul_f32 v[126:127], s[58:59], v[126:127]
	v_pk_mul_f32 v[122:123], s[58:59], v[122:123]
	v_pk_mul_f32 v[118:119], s[58:59], v[118:119]
	v_pk_mul_f32 v[130:131], s[58:59], v[114:115]
	v_mad_u64_u32 v[114:115], s[58:59], v112, s52, 0
	v_mov_b32_e32 v112, v115
	v_mad_u64_u32 v[112:113], s[58:59], v113, s52, v[112:113]
	v_pk_mul_f32 v[124:125], s[54:55], v[124:125]
	v_pk_mul_f32 v[120:121], s[54:55], v[120:121]
	v_mov_b32_e32 v115, v112
	v_pk_mul_f32 v[116:117], s[54:55], v[116:117]
	v_lshl_add_u64 v[128:129], v[114:115], 1, v[156:157]
	v_cvt_pk_bf16_f32 v112, v124, v125
	v_cvt_pk_bf16_f32 v113, v126, v127
	v_cvt_pk_bf16_f32 v114, v120, v121
	v_cvt_pk_bf16_f32 v115, v122, v123
	global_store_dwordx4 v[128:129], v[112:115], off
	s_and_b64 vcc, exec, s[8:9]
	s_nop 0
	v_cvt_pk_bf16_f32 v112, v116, v117
	v_cvt_pk_bf16_f32 v113, v118, v119
	v_cvt_pk_bf16_f32 v114, v132, v133
	v_cvt_pk_bf16_f32 v115, v130, v131
	global_store_dwordx4 v[128:129], v[112:115], off offset:64
	s_cbranch_vccnz .LBB0_203
	s_nop 0
	v_pk_mul_f32 v[114:115], v[104:105], v[104:105]
	v_pk_mul_f32 v[112:113], v[106:107], v[106:107]
	v_pk_fma_f32 v[114:115], v[108:109], v[108:109], v[114:115]
	v_pk_fma_f32 v[112:113], v[110:111], v[110:111], v[112:113]
	v_pk_fma_f32 v[114:115], v[100:101], v[100:101], v[114:115]
	v_pk_fma_f32 v[112:113], v[102:103], v[102:103], v[112:113]
	v_pk_fma_f32 v[114:115], v[96:97], v[96:97], v[114:115]
	v_pk_fma_f32 v[112:113], v[98:99], v[98:99], v[112:113]
	v_add_f32_e32 v114, v114, v115
	v_add_f32_e32 v112, v112, v114
	v_cmp_lt_i32_e32 vcc, v206, v204
	v_add_f32_e32 v112, v113, v112
	s_nop 0
	v_cndmask_b32_e32 v113, v203, v206, vcc
	v_lshlrev_b32_e32 v113, 2, v113
	ds_bpermute_b32 v113, v113, v112
	v_cmp_lt_i32_e32 vcc, v205, v204
	s_waitcnt lgkmcnt(0)
	v_add_f32_e32 v112, v112, v113
	v_cndmask_b32_e32 v113, v203, v205, vcc
	v_lshlrev_b32_e32 v113, 2, v113
	ds_bpermute_b32 v113, v113, v112
	s_waitcnt lgkmcnt(0)
	v_add_f32_e32 v112, v112, v113
	v_fmamk_f32 v112, v112, 0x3c800000, v199
	v_mul_f32_e32 v113, 0x4b800000, v112
	v_cmp_gt_f32_e32 vcc, s64, v112
	s_nop 1
	v_cndmask_b32_e32 v112, v112, v113, vcc
	v_rsq_f32_e32 v112, v112
	s_nop 0
	v_mul_f32_e32 v113, 0x45800000, v112
	v_cndmask_b32_e32 v112, v112, v113, vcc
	v_pk_mul_f32 v[108:109], v[108:109], v[112:113] op_sel_hi:[1,0]
	v_pk_mul_f32 v[110:111], v[110:111], v[112:113] op_sel_hi:[1,0]
	v_pk_mul_f32 v[104:105], v[104:105], v[112:113] op_sel_hi:[1,0]
	v_pk_mul_f32 v[106:107], v[106:107], v[112:113] op_sel_hi:[1,0]
	v_pk_mul_f32 v[100:101], v[100:101], v[112:113] op_sel_hi:[1,0]
	v_pk_mul_f32 v[102:103], v[102:103], v[112:113] op_sel_hi:[1,0]
	v_pk_mul_f32 v[96:97], v[96:97], v[112:113] op_sel_hi:[1,0]
	v_pk_mul_f32 v[98:99], v[98:99], v[112:113] op_sel_hi:[1,0]
	s_waitcnt vmcnt(6)
	v_pk_mul_f32 v[110:111], v[78:79], v[110:111]
	v_pk_mul_f32 v[108:109], v[76:77], v[108:109]
	v_pk_mul_f32 v[106:107], v[70:71], v[106:107]
	v_pk_mul_f32 v[104:105], v[68:69], v[104:105]
	v_pk_mul_f32 v[102:103], v[74:75], v[102:103]
	v_pk_mul_f32 v[100:101], v[72:73], v[100:101]
	v_pk_mul_f32 v[98:99], v[66:67], v[98:99]
	v_pk_mul_f32 v[96:97], v[64:65], v[96:97]
; __device__ __forceinline__ u32x4 pack8(const f32x4 a, const f32x4 b) { u32x4 w; w.x = pk2(a[0], a[1]); w.y = pk2(a[2], a[3]); w.z = pk2(b[0], b[1]); w.w = pk2(b[2], b[3]); return w; }
;     __device__ __forceinline__ void operator()(const f32x4 (&acc)[2][2][4][2], const Unit& u, int wr, int wc, int fr_, int fq_) const {
;     ...
;             for (int m = 0; m < 4; ++m) { const int rl = ai * HALF + wr * 64 + m * 16 + fr;
;                 f32x4 a0 = acc[ai][0][m][0], a1 = acc[ai][0][m][1], b0 = acc[ai][1][m][0], b1 = acc[ai][1][m][1];
;                 if (norm_on) { float ss = 0.f;
; #pragma unroll
;                     for (int e = 0; e < 4; ++e) ss += a0[e] * a0[e] + a1[e] * a1[e] + b0[e] * b0[e] + b1[e] * b1[e];
;                     ss += __shfl_xor(ss, 16); ss += __shfl_xor(ss, 32);
;                     const float ri = rsqrtf(ss * (1.0f / 64.0f) + 1e-6f);
;                     a0 = a0 * ri * g0[0]; a1 = a1 * ri * g1[0]; b0 = b0 * ri * g0[1]; b1 = b1 * ri * g1[1]; }
;                 if (rope_on) { const float* cp = rope + (size_t)(t0 + rl) * 32 + 8 * fq; const float* sp = cp + 2048 * 32;
;                     const f32x4 c0 = *(const f32x4*)cp, c1 = *(const f32x4*)(cp + 4), s0 = *(const f32x4*)sp, s1 = *(const f32x4*)(sp + 4);
;                     const f32x4 na0 = a0 * c0 - b0 * s0, nb0 = a0 * s0 + b0 * c0, na1 = a1 * c1 - b1 * s1, nb1 = a1 * s1 + b1 * c1;
;                     a0 = na0; b0 = nb0; a1 = na1; b1 = nb1; }
;                 a0 = a0 * qs; a1 = a1 * qs; b0 = b0 * qs; b1 = b1 * qs;
;                 bf16_t* rowp = dst + (rowbase + rl) * ld + colh;
;                 *(u32x4*)(rowp) = pack8(a0, a1); *(u32x4*)(rowp + 32) = pack8(b0, b1); }
.LBB0_203:
	s_and_b64 vcc, exec, s[10:11]
	v_add_u32_e32 v112, 32, v158
	s_cbranch_vccnz .LBB0_205
	s_waitcnt vmcnt(2)
	v_mov_b64_e32 v[114:115], v[184:185]
	v_mov_b64_e32 v[116:117], v[186:187]
	v_mov_b64_e32 v[118:119], v[194:195]
	v_mov_b64_e32 v[120:121], v[196:197]
	v_mov_b64_e32 v[122:123], v[230:231]
	v_mov_b64_e32 v[124:125], v[232:233]
	v_mov_b64_e32 v[126:127], v[234:235]
	v_mov_b64_e32 v[128:129], v[236:237]
	s_mov_b64 s[100:101], 0x1800
	v_lshl_add_u64 v[240:241], v[238:239], 0, s[100:101]
	v_lshl_add_u64 v[242:243], v[240:241], 0, s[88:89]
	global_load_dwordx4 v[184:187], v[240:241], off offset:16
	global_load_dwordx4 v[194:197], v[240:241], off
	global_load_dwordx4 v[230:233], v[242:243], off
	global_load_dwordx4 v[234:237], v[242:243], off offset:16
	v_pk_mul_f32 v[130:131], v[102:103], v[124:125]
	v_pk_mul_f32 v[134:135], v[100:101], v[122:123]
	v_pk_fma_f32 v[132:133], v[110:111], v[120:121], v[130:131] neg_lo:[0,0,1] neg_hi:[0,0,1]
	v_pk_fma_f32 v[130:131], v[108:109], v[118:119], v[134:135] neg_lo:[0,0,1] neg_hi:[0,0,1]
	v_pk_mul_f32 v[108:109], v[108:109], v[122:123]
	v_pk_mul_f32 v[110:111], v[110:111], v[124:125]
	v_pk_fma_f32 v[100:101], v[100:101], v[118:119], v[108:109]
	v_pk_mul_f32 v[108:109], v[98:99], v[128:129]
	v_pk_mul_f32 v[118:119], v[96:97], v[126:127]
	v_pk_fma_f32 v[102:103], v[102:103], v[120:121], v[110:111]
	v_pk_fma_f32 v[110:111], v[106:107], v[116:117], v[108:109] neg_lo:[0,0,1] neg_hi:[0,0,1]
	v_pk_fma_f32 v[108:109], v[104:105], v[114:115], v[118:119] neg_lo:[0,0,1] neg_hi:[0,0,1]
	v_pk_mul_f32 v[106:107], v[106:107], v[128:129]
	v_pk_mul_f32 v[104:105], v[104:105], v[126:127]
	v_pk_fma_f32 v[98:99], v[98:99], v[116:117], v[106:107]
	v_pk_fma_f32 v[96:97], v[96:97], v[114:115], v[104:105]
	v_mov_b64_e32 v[104:105], v[108:109]
	v_mov_b64_e32 v[106:107], v[110:111]
	v_mov_b64_e32 v[108:109], v[130:131]
	v_mov_b64_e32 v[110:111], v[132:133]
.LBB0_205:
	v_ashrrev_i32_e32 v113, 31, v112
	s_mov_b32 s58, s54
	s_mov_b32 s59, s54
	v_pk_mul_f32 v[116:117], s[54:55], v[96:97]
	v_lshl_add_u64 v[96:97], s[50:51], 0, v[112:113]
	v_pk_mul_f32 v[110:111], s[58:59], v[110:111]
	v_pk_mul_f32 v[106:107], s[58:59], v[106:107]
	v_pk_mul_f32 v[102:103], s[58:59], v[102:103]
	v_pk_mul_f32 v[114:115], s[58:59], v[98:99]
	v_mad_u64_u32 v[98:99], s[58:59], v96, s52, 0
	v_mov_b32_e32 v96, v99
	v_mad_u64_u32 v[96:97], s[58:59], v97, s52, v[96:97]
	v_pk_mul_f32 v[108:109], s[54:55], v[108:109]
	v_pk_mul_f32 v[104:105], s[54:55], v[104:105]
	v_mov_b32_e32 v99, v96
	v_pk_mul_f32 v[100:101], s[54:55], v[100:101]
	v_lshl_add_u64 v[112:113], v[98:99], 1, v[156:157]
	v_cvt_pk_bf16_f32 v96, v108, v109
	v_cvt_pk_bf16_f32 v97, v110, v111
	v_cvt_pk_bf16_f32 v98, v104, v105
	v_cvt_pk_bf16_f32 v99, v106, v107
	global_store_dwordx4 v[112:113], v[96:99], off
	s_and_b64 vcc, exec, s[8:9]
	s_nop 0
	v_cvt_pk_bf16_f32 v96, v100, v101
	v_cvt_pk_bf16_f32 v97, v102, v103
	v_cvt_pk_bf16_f32 v98, v116, v117
	v_cvt_pk_bf16_f32 v99, v114, v115
	global_store_dwordx4 v[112:113], v[96:99], off offset:64
	s_cbranch_vccnz .LBB0_207
	s_nop 0
	v_pk_mul_f32 v[98:99], v[88:89], v[88:89]
	v_pk_mul_f32 v[96:97], v[90:91], v[90:91]
	v_pk_fma_f32 v[98:99], v[92:93], v[92:93], v[98:99]
	v_pk_fma_f32 v[96:97], v[94:95], v[94:95], v[96:97]
	v_pk_fma_f32 v[98:99], v[84:85], v[84:85], v[98:99]
	v_pk_fma_f32 v[96:97], v[86:87], v[86:87], v[96:97]
	v_pk_fma_f32 v[98:99], v[80:81], v[80:81], v[98:99]
	v_pk_fma_f32 v[96:97], v[82:83], v[82:83], v[96:97]
	v_add_f32_e32 v98, v98, v99
	v_add_f32_e32 v96, v96, v98
	v_cmp_lt_i32_e32 vcc, v206, v204
	v_add_f32_e32 v96, v97, v96
	s_nop 0
	v_cndmask_b32_e32 v97, v203, v206, vcc
	v_lshlrev_b32_e32 v97, 2, v97
	ds_bpermute_b32 v97, v97, v96
	v_cmp_lt_i32_e32 vcc, v205, v204
	s_waitcnt lgkmcnt(0)
	v_add_f32_e32 v96, v96, v97
	v_cndmask_b32_e32 v97, v203, v205, vcc
	v_lshlrev_b32_e32 v97, 2, v97
	ds_bpermute_b32 v97, v97, v96
	s_waitcnt lgkmcnt(0)
	v_add_f32_e32 v96, v96, v97
	v_fmamk_f32 v96, v96, 0x3c800000, v199
	v_mul_f32_e32 v97, 0x4b800000, v96
	v_cmp_gt_f32_e32 vcc, s64, v96
	s_nop 1
	v_cndmask_b32_e32 v96, v96, v97, vcc
	v_rsq_f32_e32 v96, v96
	s_nop 0
	v_mul_f32_e32 v97, 0x45800000, v96
	v_cndmask_b32_e32 v96, v96, v97, vcc
	v_pk_mul_f32 v[92:93], v[92:93], v[96:97] op_sel_hi:[1,0]
	v_pk_mul_f32 v[94:95], v[94:95], v[96:97] op_sel_hi:[1,0]
	v_pk_mul_f32 v[88:89], v[88:89], v[96:97] op_sel_hi:[1,0]
	v_pk_mul_f32 v[90:91], v[90:91], v[96:97] op_sel_hi:[1,0]
	v_pk_mul_f32 v[84:85], v[84:85], v[96:97] op_sel_hi:[1,0]
	v_pk_mul_f32 v[86:87], v[86:87], v[96:97] op_sel_hi:[1,0]
	v_pk_mul_f32 v[80:81], v[80:81], v[96:97] op_sel_hi:[1,0]
	v_pk_mul_f32 v[82:83], v[82:83], v[96:97] op_sel_hi:[1,0]
	s_waitcnt vmcnt(6)
	v_pk_mul_f32 v[94:95], v[78:79], v[94:95]
	v_pk_mul_f32 v[92:93], v[76:77], v[92:93]
	v_pk_mul_f32 v[90:91], v[70:71], v[90:91]
	v_pk_mul_f32 v[88:89], v[68:69], v[88:89]
	v_pk_mul_f32 v[86:87], v[74:75], v[86:87]
	v_pk_mul_f32 v[84:85], v[72:73], v[84:85]
	v_pk_mul_f32 v[82:83], v[66:67], v[82:83]
	v_pk_mul_f32 v[80:81], v[64:65], v[80:81]
; __device__ __forceinline__ u32x4 pack8(const f32x4 a, const f32x4 b) { u32x4 w; w.x = pk2(a[0], a[1]); w.y = pk2(a[2], a[3]); w.z = pk2(b[0], b[1]); w.w = pk2(b[2], b[3]); return w; }
;     __device__ __forceinline__ void operator()(const f32x4 (&acc)[2][2][4][2], const Unit& u, int wr, int wc, int fr_, int fq_) const {
;     ...
;             for (int m = 0; m < 4; ++m) { const int rl = ai * HALF + wr * 64 + m * 16 + fr;
;                 f32x4 a0 = acc[ai][0][m][0], a1 = acc[ai][0][m][1], b0 = acc[ai][1][m][0], b1 = acc[ai][1][m][1];
;                 if (norm_on) { float ss = 0.f;
; #pragma unroll
;                     for (int e = 0; e < 4; ++e) ss += a0[e] * a0[e] + a1[e] * a1[e] + b0[e] * b0[e] + b1[e] * b1[e];
;                     ss += __shfl_xor(ss, 16); ss += __shfl_xor(ss, 32);
;                     const float ri = rsqrtf(ss * (1.0f / 64.0f) + 1e-6f);
;                     a0 = a0 * ri * g0[0]; a1 = a1 * ri * g1[0]; b0 = b0 * ri * g0[1]; b1 = b1 * ri * g1[1]; }
;                 if (rope_on) { const float* cp = rope + (size_t)(t0 + rl) * 32 + 8 * fq; const float* sp = cp + 2048 * 32;
;                     const f32x4 c0 = *(const f32x4*)cp, c1 = *(const f32x4*)(cp + 4), s0 = *(const f32x4*)sp, s1 = *(const f32x4*)(sp + 4);
;                     const f32x4 na0 = a0 * c0 - b0 * s0, nb0 = a0 * s0 + b0 * c0, na1 = a1 * c1 - b1 * s1, nb1 = a1 * s1 + b1 * c1;
;                     a0 = na0; b0 = nb0; a1 = na1; b1 = nb1; }
;                 a0 = a0 * qs; a1 = a1 * qs; b0 = b0 * qs; b1 = b1 * qs;
;                 bf16_t* rowp = dst + (rowbase + rl) * ld + colh;
;                 *(u32x4*)(rowp) = pack8(a0, a1); *(u32x4*)(rowp + 32) = pack8(b0, b1); }
.LBB0_207:
	s_and_b64 vcc, exec, s[10:11]
	v_add_u32_e32 v96, 48, v158
	s_cbranch_vccnz .LBB0_209
	s_waitcnt vmcnt(2)
	v_mov_b64_e32 v[98:99], v[184:185]
	v_mov_b64_e32 v[100:101], v[186:187]
	v_mov_b64_e32 v[102:103], v[194:195]
	v_mov_b64_e32 v[104:105], v[196:197]
	v_mov_b64_e32 v[106:107], v[230:231]
	v_mov_b64_e32 v[108:109], v[232:233]
	v_mov_b64_e32 v[110:111], v[234:235]
	v_mov_b64_e32 v[112:113], v[236:237]
	s_mov_b64 s[100:101], 0x4000
	v_lshl_add_u64 v[240:241], v[238:239], 0, s[100:101]
	v_lshl_add_u64 v[242:243], v[240:241], 0, s[88:89]
	global_load_dwordx4 v[184:187], v[240:241], off offset:16
	global_load_dwordx4 v[194:197], v[240:241], off
	global_load_dwordx4 v[230:233], v[242:243], off
	global_load_dwordx4 v[234:237], v[242:243], off offset:16
	v_pk_mul_f32 v[114:115], v[86:87], v[108:109]
	v_pk_mul_f32 v[118:119], v[84:85], v[106:107]
	v_pk_fma_f32 v[116:117], v[94:95], v[104:105], v[114:115] neg_lo:[0,0,1] neg_hi:[0,0,1]
	v_pk_fma_f32 v[114:115], v[92:93], v[102:103], v[118:119] neg_lo:[0,0,1] neg_hi:[0,0,1]
	v_pk_mul_f32 v[92:93], v[92:93], v[106:107]
	v_pk_mul_f32 v[94:95], v[94:95], v[108:109]
	v_pk_fma_f32 v[84:85], v[84:85], v[102:103], v[92:93]
	v_pk_mul_f32 v[92:93], v[82:83], v[112:113]
	v_pk_mul_f32 v[102:103], v[80:81], v[110:111]
	v_pk_fma_f32 v[86:87], v[86:87], v[104:105], v[94:95]
	v_pk_fma_f32 v[94:95], v[90:91], v[100:101], v[92:93] neg_lo:[0,0,1] neg_hi:[0,0,1]
	v_pk_fma_f32 v[92:93], v[88:89], v[98:99], v[102:103] neg_lo:[0,0,1] neg_hi:[0,0,1]
	v_pk_mul_f32 v[90:91], v[90:91], v[112:113]
	v_pk_mul_f32 v[88:89], v[88:89], v[110:111]
	v_pk_fma_f32 v[82:83], v[82:83], v[100:101], v[90:91]
	v_pk_fma_f32 v[80:81], v[80:81], v[98:99], v[88:89]
	v_mov_b64_e32 v[88:89], v[92:93]
	v_mov_b64_e32 v[90:91], v[94:95]
	v_mov_b64_e32 v[92:93], v[114:115]
	v_mov_b64_e32 v[94:95], v[116:117]
.LBB0_209:
	v_ashrrev_i32_e32 v97, 31, v96
	s_mov_b32 s58, s54
	s_mov_b32 s59, s54
	v_pk_mul_f32 v[100:101], s[54:55], v[80:81]
	v_lshl_add_u64 v[80:81], s[50:51], 0, v[96:97]
	v_pk_mul_f32 v[94:95], s[58:59], v[94:95]
	v_pk_mul_f32 v[90:91], s[58:59], v[90:91]
	v_pk_mul_f32 v[86:87], s[58:59], v[86:87]
	v_pk_mul_f32 v[98:99], s[58:59], v[82:83]
	v_mad_u64_u32 v[82:83], s[58:59], v80, s52, 0
	v_mov_b32_e32 v80, v83
	v_mad_u64_u32 v[80:81], s[58:59], v81, s52, v[80:81]
	v_pk_mul_f32 v[92:93], s[54:55], v[92:93]
	v_pk_mul_f32 v[88:89], s[54:55], v[88:89]
	v_mov_b32_e32 v83, v80
	v_pk_mul_f32 v[84:85], s[54:55], v[84:85]
	v_lshl_add_u64 v[96:97], v[82:83], 1, v[156:157]
	v_cvt_pk_bf16_f32 v80, v92, v93
	v_cvt_pk_bf16_f32 v81, v94, v95
	v_cvt_pk_bf16_f32 v82, v88, v89
	v_cvt_pk_bf16_f32 v83, v90, v91
	global_store_dwordx4 v[96:97], v[80:83], off
	s_and_b64 vcc, exec, s[8:9]
	s_nop 0
	v_cvt_pk_bf16_f32 v80, v84, v85
	v_cvt_pk_bf16_f32 v81, v86, v87
	v_cvt_pk_bf16_f32 v82, v100, v101
	v_cvt_pk_bf16_f32 v83, v98, v99
	global_store_dwordx4 v[96:97], v[80:83], off offset:64
	s_cbranch_vccnz .LBB0_211
	s_nop 0
	v_pk_mul_f32 v[82:83], v[56:57], v[56:57]
	v_pk_mul_f32 v[80:81], v[58:59], v[58:59]
	v_pk_fma_f32 v[82:83], v[60:61], v[60:61], v[82:83]
	v_pk_fma_f32 v[80:81], v[62:63], v[62:63], v[80:81]
	v_pk_fma_f32 v[82:83], v[52:53], v[52:53], v[82:83]
	v_pk_fma_f32 v[80:81], v[54:55], v[54:55], v[80:81]
	v_pk_fma_f32 v[82:83], v[48:49], v[48:49], v[82:83]
	v_pk_fma_f32 v[80:81], v[50:51], v[50:51], v[80:81]
	v_add_f32_e32 v82, v82, v83
	v_add_f32_e32 v80, v80, v82
	v_cmp_lt_i32_e32 vcc, v206, v204
	v_add_f32_e32 v80, v81, v80
	s_nop 0
	v_cndmask_b32_e32 v81, v203, v206, vcc
	v_lshlrev_b32_e32 v81, 2, v81
	ds_bpermute_b32 v81, v81, v80
	v_cmp_lt_i32_e32 vcc, v205, v204
	s_waitcnt lgkmcnt(0)
	v_add_f32_e32 v80, v80, v81
	v_cndmask_b32_e32 v81, v203, v205, vcc
	v_lshlrev_b32_e32 v81, 2, v81
	ds_bpermute_b32 v81, v81, v80
	s_waitcnt lgkmcnt(0)
	v_add_f32_e32 v80, v80, v81
	v_fmamk_f32 v80, v80, 0x3c800000, v199
	v_mul_f32_e32 v81, 0x4b800000, v80
	v_cmp_gt_f32_e32 vcc, s64, v80
	s_nop 1
	v_cndmask_b32_e32 v80, v80, v81, vcc
	v_rsq_f32_e32 v80, v80
	s_nop 0
	v_mul_f32_e32 v81, 0x45800000, v80
	v_cndmask_b32_e32 v80, v80, v81, vcc
	v_pk_mul_f32 v[60:61], v[60:61], v[80:81] op_sel_hi:[1,0]
	v_pk_mul_f32 v[62:63], v[62:63], v[80:81] op_sel_hi:[1,0]
	v_pk_mul_f32 v[56:57], v[56:57], v[80:81] op_sel_hi:[1,0]
	v_pk_mul_f32 v[58:59], v[58:59], v[80:81] op_sel_hi:[1,0]
	v_pk_mul_f32 v[52:53], v[52:53], v[80:81] op_sel_hi:[1,0]
	v_pk_mul_f32 v[54:55], v[54:55], v[80:81] op_sel_hi:[1,0]
	v_pk_mul_f32 v[48:49], v[48:49], v[80:81] op_sel_hi:[1,0]
	v_pk_mul_f32 v[50:51], v[50:51], v[80:81] op_sel_hi:[1,0]
	s_waitcnt vmcnt(6)
	v_pk_mul_f32 v[62:63], v[78:79], v[62:63]
	v_pk_mul_f32 v[60:61], v[76:77], v[60:61]
	v_pk_mul_f32 v[58:59], v[70:71], v[58:59]
	v_pk_mul_f32 v[56:57], v[68:69], v[56:57]
	v_pk_mul_f32 v[54:55], v[74:75], v[54:55]
	v_pk_mul_f32 v[52:53], v[72:73], v[52:53]
	v_pk_mul_f32 v[50:51], v[66:67], v[50:51]
	v_pk_mul_f32 v[48:49], v[64:65], v[48:49]
; __device__ __forceinline__ u32x4 pack8(const f32x4 a, const f32x4 b) { u32x4 w; w.x = pk2(a[0], a[1]); w.y = pk2(a[2], a[3]); w.z = pk2(b[0], b[1]); w.w = pk2(b[2], b[3]); return w; }
;     __device__ __forceinline__ void operator()(const f32x4 (&acc)[2][2][4][2], const Unit& u, int wr, int wc, int fr_, int fq_) const {
;     ...
;             for (int m = 0; m < 4; ++m) { const int rl = ai * HALF + wr * 64 + m * 16 + fr;
;                 f32x4 a0 = acc[ai][0][m][0], a1 = acc[ai][0][m][1], b0 = acc[ai][1][m][0], b1 = acc[ai][1][m][1];
;                 if (norm_on) { float ss = 0.f;
; #pragma unroll
;                     for (int e = 0; e < 4; ++e) ss += a0[e] * a0[e] + a1[e] * a1[e] + b0[e] * b0[e] + b1[e] * b1[e];
;                     ss += __shfl_xor(ss, 16); ss += __shfl_xor(ss, 32);
;                     const float ri = rsqrtf(ss * (1.0f / 64.0f) + 1e-6f);
;                     a0 = a0 * ri * g0[0]; a1 = a1 * ri * g1[0]; b0 = b0 * ri * g0[1]; b1 = b1 * ri * g1[1]; }
;                 if (rope_on) { const float* cp = rope + (size_t)(t0 + rl) * 32 + 8 * fq; const float* sp = cp + 2048 * 32;
;                     const f32x4 c0 = *(const f32x4*)cp, c1 = *(const f32x4*)(cp + 4), s0 = *(const f32x4*)sp, s1 = *(const f32x4*)(sp + 4);
;                     const f32x4 na0 = a0 * c0 - b0 * s0, nb0 = a0 * s0 + b0 * c0, na1 = a1 * c1 - b1 * s1, nb1 = a1 * s1 + b1 * c1;
;                     a0 = na0; b0 = nb0; a1 = na1; b1 = nb1; }
;                 a0 = a0 * qs; a1 = a1 * qs; b0 = b0 * qs; b1 = b1 * qs;
;                 bf16_t* rowp = dst + (rowbase + rl) * ld + colh;
;                 *(u32x4*)(rowp) = pack8(a0, a1); *(u32x4*)(rowp + 32) = pack8(b0, b1); }
.LBB0_211:
	s_and_b64 vcc, exec, s[10:11]
	v_add_u32_e32 v80, 0x80, v158
	s_cbranch_vccnz .LBB0_213
	s_waitcnt vmcnt(2)
	v_mov_b64_e32 v[82:83], v[184:185]
	v_mov_b64_e32 v[84:85], v[186:187]
	v_mov_b64_e32 v[86:87], v[194:195]
	v_mov_b64_e32 v[88:89], v[196:197]
	v_mov_b64_e32 v[90:91], v[230:231]
	v_mov_b64_e32 v[92:93], v[232:233]
	v_mov_b64_e32 v[94:95], v[234:235]
	v_mov_b64_e32 v[96:97], v[236:237]
	s_mov_b64 s[100:101], 0x4800
	v_lshl_add_u64 v[240:241], v[238:239], 0, s[100:101]
	v_lshl_add_u64 v[242:243], v[240:241], 0, s[88:89]
	global_load_dwordx4 v[184:187], v[240:241], off offset:16
	global_load_dwordx4 v[194:197], v[240:241], off
	global_load_dwordx4 v[230:233], v[242:243], off
	global_load_dwordx4 v[234:237], v[242:243], off offset:16
	v_pk_mul_f32 v[98:99], v[54:55], v[92:93]
	v_pk_mul_f32 v[102:103], v[52:53], v[90:91]
	v_pk_fma_f32 v[100:101], v[62:63], v[88:89], v[98:99] neg_lo:[0,0,1] neg_hi:[0,0,1]
	v_pk_fma_f32 v[98:99], v[60:61], v[86:87], v[102:103] neg_lo:[0,0,1] neg_hi:[0,0,1]
	v_pk_mul_f32 v[60:61], v[60:61], v[90:91]
	v_pk_mul_f32 v[62:63], v[62:63], v[92:93]
	v_pk_fma_f32 v[52:53], v[52:53], v[86:87], v[60:61]
	v_pk_mul_f32 v[60:61], v[50:51], v[96:97]
	v_pk_mul_f32 v[86:87], v[48:49], v[94:95]
	v_pk_fma_f32 v[54:55], v[54:55], v[88:89], v[62:63]
	v_pk_fma_f32 v[62:63], v[58:59], v[84:85], v[60:61] neg_lo:[0,0,1] neg_hi:[0,0,1]
	v_pk_fma_f32 v[60:61], v[56:57], v[82:83], v[86:87] neg_lo:[0,0,1] neg_hi:[0,0,1]
	v_pk_mul_f32 v[58:59], v[58:59], v[96:97]
	v_pk_mul_f32 v[56:57], v[56:57], v[94:95]
	v_pk_fma_f32 v[50:51], v[50:51], v[84:85], v[58:59]
	v_pk_fma_f32 v[48:49], v[48:49], v[82:83], v[56:57]
	v_mov_b64_e32 v[56:57], v[60:61]
	v_mov_b64_e32 v[58:59], v[62:63]
	v_mov_b64_e32 v[60:61], v[98:99]
	v_mov_b64_e32 v[62:63], v[100:101]
.LBB0_213:
	v_ashrrev_i32_e32 v81, 31, v80
	s_mov_b32 s58, s54
	s_mov_b32 s59, s54
	v_pk_mul_f32 v[84:85], s[54:55], v[48:49]
	v_lshl_add_u64 v[48:49], s[50:51], 0, v[80:81]
	v_pk_mul_f32 v[62:63], s[58:59], v[62:63]
	v_pk_mul_f32 v[58:59], s[58:59], v[58:59]
	v_pk_mul_f32 v[54:55], s[58:59], v[54:55]
	v_pk_mul_f32 v[82:83], s[58:59], v[50:51]
	v_mad_u64_u32 v[50:51], s[58:59], v48, s52, 0
	v_mov_b32_e32 v48, v51
	v_mad_u64_u32 v[48:49], s[58:59], v49, s52, v[48:49]
	v_pk_mul_f32 v[60:61], s[54:55], v[60:61]
	v_pk_mul_f32 v[56:57], s[54:55], v[56:57]
	v_mov_b32_e32 v51, v48
	v_pk_mul_f32 v[52:53], s[54:55], v[52:53]
	v_lshl_add_u64 v[80:81], v[50:51], 1, v[156:157]
	v_cvt_pk_bf16_f32 v48, v60, v61
	v_cvt_pk_bf16_f32 v49, v62, v63
	v_cvt_pk_bf16_f32 v50, v56, v57
	v_cvt_pk_bf16_f32 v51, v58, v59
	global_store_dwordx4 v[80:81], v[48:51], off
	s_and_b64 vcc, exec, s[8:9]
	s_nop 0
	v_cvt_pk_bf16_f32 v48, v52, v53
	v_cvt_pk_bf16_f32 v49, v54, v55
	v_cvt_pk_bf16_f32 v50, v84, v85
	v_cvt_pk_bf16_f32 v51, v82, v83
	global_store_dwordx4 v[80:81], v[48:51], off offset:64
	s_cbranch_vccnz .LBB0_215
	s_nop 0
	v_pk_mul_f32 v[50:51], v[40:41], v[40:41]
	v_pk_mul_f32 v[48:49], v[42:43], v[42:43]
	v_pk_fma_f32 v[50:51], v[44:45], v[44:45], v[50:51]
	v_pk_fma_f32 v[48:49], v[46:47], v[46:47], v[48:49]
	v_pk_fma_f32 v[50:51], v[36:37], v[36:37], v[50:51]
	v_pk_fma_f32 v[48:49], v[38:39], v[38:39], v[48:49]
	v_pk_fma_f32 v[50:51], v[32:33], v[32:33], v[50:51]
	v_pk_fma_f32 v[48:49], v[34:35], v[34:35], v[48:49]
	v_add_f32_e32 v50, v50, v51
	v_add_f32_e32 v48, v48, v50
	v_cmp_lt_i32_e32 vcc, v206, v204
	v_add_f32_e32 v48, v49, v48
	s_nop 0
	v_cndmask_b32_e32 v49, v203, v206, vcc
	v_lshlrev_b32_e32 v49, 2, v49
	ds_bpermute_b32 v49, v49, v48
	v_cmp_lt_i32_e32 vcc, v205, v204
	s_waitcnt lgkmcnt(0)
	v_add_f32_e32 v48, v48, v49
	v_cndmask_b32_e32 v49, v203, v205, vcc
	v_lshlrev_b32_e32 v49, 2, v49
	ds_bpermute_b32 v49, v49, v48
	s_waitcnt lgkmcnt(0)
	v_add_f32_e32 v48, v48, v49
	v_fmamk_f32 v48, v48, 0x3c800000, v199
	v_mul_f32_e32 v49, 0x4b800000, v48
	v_cmp_gt_f32_e32 vcc, s64, v48
	s_nop 1
	v_cndmask_b32_e32 v48, v48, v49, vcc
	v_rsq_f32_e32 v48, v48
	s_nop 0
	v_mul_f32_e32 v49, 0x45800000, v48
	v_cndmask_b32_e32 v48, v48, v49, vcc
	v_pk_mul_f32 v[44:45], v[44:45], v[48:49] op_sel_hi:[1,0]
	v_pk_mul_f32 v[46:47], v[46:47], v[48:49] op_sel_hi:[1,0]
	v_pk_mul_f32 v[40:41], v[40:41], v[48:49] op_sel_hi:[1,0]
	v_pk_mul_f32 v[42:43], v[42:43], v[48:49] op_sel_hi:[1,0]
	v_pk_mul_f32 v[36:37], v[36:37], v[48:49] op_sel_hi:[1,0]
	v_pk_mul_f32 v[38:39], v[38:39], v[48:49] op_sel_hi:[1,0]
	v_pk_mul_f32 v[32:33], v[32:33], v[48:49] op_sel_hi:[1,0]
	v_pk_mul_f32 v[34:35], v[34:35], v[48:49] op_sel_hi:[1,0]
	s_waitcnt vmcnt(6)
	v_pk_mul_f32 v[46:47], v[78:79], v[46:47]
	v_pk_mul_f32 v[44:45], v[76:77], v[44:45]
	v_pk_mul_f32 v[42:43], v[70:71], v[42:43]
	v_pk_mul_f32 v[40:41], v[68:69], v[40:41]
	v_pk_mul_f32 v[38:39], v[74:75], v[38:39]
	v_pk_mul_f32 v[36:37], v[72:73], v[36:37]
	v_pk_mul_f32 v[34:35], v[66:67], v[34:35]
	v_pk_mul_f32 v[32:33], v[64:65], v[32:33]
; __device__ __forceinline__ u32x4 pack8(const f32x4 a, const f32x4 b) { u32x4 w; w.x = pk2(a[0], a[1]); w.y = pk2(a[2], a[3]); w.z = pk2(b[0], b[1]); w.w = pk2(b[2], b[3]); return w; }
;     __device__ __forceinline__ void operator()(const f32x4 (&acc)[2][2][4][2], const Unit& u, int wr, int wc, int fr_, int fq_) const {
;     ...
;             for (int m = 0; m < 4; ++m) { const int rl = ai * HALF + wr * 64 + m * 16 + fr;
;                 f32x4 a0 = acc[ai][0][m][0], a1 = acc[ai][0][m][1], b0 = acc[ai][1][m][0], b1 = acc[ai][1][m][1];
;                 if (norm_on) { float ss = 0.f;
; #pragma unroll
;                     for (int e = 0; e < 4; ++e) ss += a0[e] * a0[e] + a1[e] * a1[e] + b0[e] * b0[e] + b1[e] * b1[e];
;                     ss += __shfl_xor(ss, 16); ss += __shfl_xor(ss, 32);
;                     const float ri = rsqrtf(ss * (1.0f / 64.0f) + 1e-6f);
;                     a0 = a0 * ri * g0[0]; a1 = a1 * ri * g1[0]; b0 = b0 * ri * g0[1]; b1 = b1 * ri * g1[1]; }
;                 if (rope_on) { const float* cp = rope + (size_t)(t0 + rl) * 32 + 8 * fq; const float* sp = cp + 2048 * 32;
;                     const f32x4 c0 = *(const f32x4*)cp, c1 = *(const f32x4*)(cp + 4), s0 = *(const f32x4*)sp, s1 = *(const f32x4*)(sp + 4);
;                     const f32x4 na0 = a0 * c0 - b0 * s0, nb0 = a0 * s0 + b0 * c0, na1 = a1 * c1 - b1 * s1, nb1 = a1 * s1 + b1 * c1;
;                     a0 = na0; b0 = nb0; a1 = na1; b1 = nb1; }
;                 a0 = a0 * qs; a1 = a1 * qs; b0 = b0 * qs; b1 = b1 * qs;
;                 bf16_t* rowp = dst + (rowbase + rl) * ld + colh;
;                 *(u32x4*)(rowp) = pack8(a0, a1); *(u32x4*)(rowp + 32) = pack8(b0, b1); }
.LBB0_215:
	s_and_b64 vcc, exec, s[10:11]
	v_add_u32_e32 v48, 0x90, v158
	s_cbranch_vccnz .LBB0_217
	s_waitcnt vmcnt(2)
	v_mov_b64_e32 v[50:51], v[184:185]
	v_mov_b64_e32 v[52:53], v[186:187]
	v_mov_b64_e32 v[54:55], v[194:195]
	v_mov_b64_e32 v[56:57], v[196:197]
	v_mov_b64_e32 v[58:59], v[230:231]
	v_mov_b64_e32 v[60:61], v[232:233]
	v_mov_b64_e32 v[80:81], v[234:235]
	v_mov_b64_e32 v[82:83], v[236:237]
	s_mov_b64 s[100:101], 0x5000
	v_lshl_add_u64 v[240:241], v[238:239], 0, s[100:101]
	v_lshl_add_u64 v[242:243], v[240:241], 0, s[88:89]
	global_load_dwordx4 v[184:187], v[240:241], off offset:16
	global_load_dwordx4 v[194:197], v[240:241], off
	global_load_dwordx4 v[230:233], v[242:243], off
	global_load_dwordx4 v[234:237], v[242:243], off offset:16
	v_pk_mul_f32 v[84:85], v[36:37], v[58:59]
	v_pk_mul_f32 v[62:63], v[38:39], v[60:61]
	v_pk_fma_f32 v[84:85], v[44:45], v[54:55], v[84:85] neg_lo:[0,0,1] neg_hi:[0,0,1]
	v_pk_mul_f32 v[44:45], v[44:45], v[58:59]
	v_pk_fma_f32 v[86:87], v[46:47], v[56:57], v[62:63] neg_lo:[0,0,1] neg_hi:[0,0,1]
	v_pk_mul_f32 v[46:47], v[46:47], v[60:61]
	v_pk_fma_f32 v[36:37], v[36:37], v[54:55], v[44:45]
	v_pk_mul_f32 v[44:45], v[34:35], v[82:83]
	v_pk_mul_f32 v[54:55], v[32:33], v[80:81]
	v_pk_fma_f32 v[38:39], v[38:39], v[56:57], v[46:47]
	v_pk_fma_f32 v[46:47], v[42:43], v[52:53], v[44:45] neg_lo:[0,0,1] neg_hi:[0,0,1]
	v_pk_fma_f32 v[44:45], v[40:41], v[50:51], v[54:55] neg_lo:[0,0,1] neg_hi:[0,0,1]
	v_pk_mul_f32 v[42:43], v[42:43], v[82:83]
	v_pk_mul_f32 v[40:41], v[40:41], v[80:81]
	v_pk_fma_f32 v[34:35], v[34:35], v[52:53], v[42:43]
	v_pk_fma_f32 v[32:33], v[32:33], v[50:51], v[40:41]
	v_mov_b64_e32 v[40:41], v[44:45]
	v_mov_b64_e32 v[42:43], v[46:47]
	v_mov_b64_e32 v[44:45], v[84:85]
	v_mov_b64_e32 v[46:47], v[86:87]
.LBB0_217:
	v_ashrrev_i32_e32 v49, 31, v48
	s_mov_b32 s58, s54
	s_mov_b32 s59, s54
	v_pk_mul_f32 v[52:53], s[54:55], v[32:33]
	v_lshl_add_u64 v[32:33], s[50:51], 0, v[48:49]
	v_pk_mul_f32 v[46:47], s[58:59], v[46:47]
	v_pk_mul_f32 v[42:43], s[58:59], v[42:43]
	v_pk_mul_f32 v[38:39], s[58:59], v[38:39]
	v_pk_mul_f32 v[50:51], s[58:59], v[34:35]
	v_mad_u64_u32 v[34:35], s[58:59], v32, s52, 0
	v_mov_b32_e32 v32, v35
	v_mad_u64_u32 v[32:33], s[58:59], v33, s52, v[32:33]
	v_pk_mul_f32 v[44:45], s[54:55], v[44:45]
	v_pk_mul_f32 v[40:41], s[54:55], v[40:41]
	v_mov_b32_e32 v35, v32
	v_pk_mul_f32 v[36:37], s[54:55], v[36:37]
	v_lshl_add_u64 v[48:49], v[34:35], 1, v[156:157]
	v_cvt_pk_bf16_f32 v32, v44, v45
	v_cvt_pk_bf16_f32 v33, v46, v47
	v_cvt_pk_bf16_f32 v34, v40, v41
	v_cvt_pk_bf16_f32 v35, v42, v43
	global_store_dwordx4 v[48:49], v[32:35], off
	s_and_b64 vcc, exec, s[8:9]
	s_nop 0
	v_cvt_pk_bf16_f32 v32, v36, v37
	v_cvt_pk_bf16_f32 v33, v38, v39
	v_cvt_pk_bf16_f32 v34, v52, v53
	v_cvt_pk_bf16_f32 v35, v50, v51
	global_store_dwordx4 v[48:49], v[32:35], off offset:64
	s_cbranch_vccnz .LBB0_219
	s_nop 0
	v_pk_mul_f32 v[34:35], v[24:25], v[24:25]
	v_pk_mul_f32 v[32:33], v[26:27], v[26:27]
	v_pk_fma_f32 v[34:35], v[28:29], v[28:29], v[34:35]
	v_pk_fma_f32 v[32:33], v[30:31], v[30:31], v[32:33]
	v_pk_fma_f32 v[34:35], v[20:21], v[20:21], v[34:35]
	v_pk_fma_f32 v[32:33], v[22:23], v[22:23], v[32:33]
	v_pk_fma_f32 v[34:35], v[16:17], v[16:17], v[34:35]
	v_pk_fma_f32 v[32:33], v[18:19], v[18:19], v[32:33]
	v_add_f32_e32 v34, v34, v35
	v_add_f32_e32 v32, v32, v34
	v_cmp_lt_i32_e32 vcc, v206, v204
	v_add_f32_e32 v32, v33, v32
	s_nop 0
	v_cndmask_b32_e32 v33, v203, v206, vcc
	v_lshlrev_b32_e32 v33, 2, v33
	ds_bpermute_b32 v33, v33, v32
	v_cmp_lt_i32_e32 vcc, v205, v204
	s_waitcnt lgkmcnt(0)
	v_add_f32_e32 v32, v32, v33
	v_cndmask_b32_e32 v33, v203, v205, vcc
	v_lshlrev_b32_e32 v33, 2, v33
	ds_bpermute_b32 v33, v33, v32
	s_waitcnt lgkmcnt(0)
	v_add_f32_e32 v32, v32, v33
	v_fmamk_f32 v32, v32, 0x3c800000, v199
	v_mul_f32_e32 v33, 0x4b800000, v32
	v_cmp_gt_f32_e32 vcc, s64, v32
	s_nop 1
	v_cndmask_b32_e32 v32, v32, v33, vcc
	v_rsq_f32_e32 v32, v32
	s_nop 0
	v_mul_f32_e32 v33, 0x45800000, v32
	v_cndmask_b32_e32 v32, v32, v33, vcc
	v_pk_mul_f32 v[28:29], v[28:29], v[32:33] op_sel_hi:[1,0]
	v_pk_mul_f32 v[30:31], v[30:31], v[32:33] op_sel_hi:[1,0]
	v_pk_mul_f32 v[24:25], v[24:25], v[32:33] op_sel_hi:[1,0]
	v_pk_mul_f32 v[26:27], v[26:27], v[32:33] op_sel_hi:[1,0]
	v_pk_mul_f32 v[20:21], v[20:21], v[32:33] op_sel_hi:[1,0]
	v_pk_mul_f32 v[22:23], v[22:23], v[32:33] op_sel_hi:[1,0]
	v_pk_mul_f32 v[16:17], v[16:17], v[32:33] op_sel_hi:[1,0]
	v_pk_mul_f32 v[18:19], v[18:19], v[32:33] op_sel_hi:[1,0]
	s_waitcnt vmcnt(6)
	v_pk_mul_f32 v[30:31], v[78:79], v[30:31]
	v_pk_mul_f32 v[28:29], v[76:77], v[28:29]
	v_pk_mul_f32 v[26:27], v[70:71], v[26:27]
	v_pk_mul_f32 v[24:25], v[68:69], v[24:25]
	v_pk_mul_f32 v[22:23], v[74:75], v[22:23]
	v_pk_mul_f32 v[20:21], v[72:73], v[20:21]
	v_pk_mul_f32 v[18:19], v[66:67], v[18:19]
	v_pk_mul_f32 v[16:17], v[64:65], v[16:17]
; __device__ __forceinline__ u32x4 pack8(const f32x4 a, const f32x4 b) { u32x4 w; w.x = pk2(a[0], a[1]); w.y = pk2(a[2], a[3]); w.z = pk2(b[0], b[1]); w.w = pk2(b[2], b[3]); return w; }
;     __device__ __forceinline__ void operator()(const f32x4 (&acc)[2][2][4][2], const Unit& u, int wr, int wc, int fr_, int fq_) const {
;     ...
;             for (int m = 0; m < 4; ++m) { const int rl = ai * HALF + wr * 64 + m * 16 + fr;
;                 f32x4 a0 = acc[ai][0][m][0], a1 = acc[ai][0][m][1], b0 = acc[ai][1][m][0], b1 = acc[ai][1][m][1];
;                 if (norm_on) { float ss = 0.f;
; #pragma unroll
;                     for (int e = 0; e < 4; ++e) ss += a0[e] * a0[e] + a1[e] * a1[e] + b0[e] * b0[e] + b1[e] * b1[e];
;                     ss += __shfl_xor(ss, 16); ss += __shfl_xor(ss, 32);
;                     const float ri = rsqrtf(ss * (1.0f / 64.0f) + 1e-6f);
;                     a0 = a0 * ri * g0[0]; a1 = a1 * ri * g1[0]; b0 = b0 * ri * g0[1]; b1 = b1 * ri * g1[1]; }
;                 if (rope_on) { const float* cp = rope + (size_t)(t0 + rl) * 32 + 8 * fq; const float* sp = cp + 2048 * 32;
;                     const f32x4 c0 = *(const f32x4*)cp, c1 = *(const f32x4*)(cp + 4), s0 = *(const f32x4*)sp, s1 = *(const f32x4*)(sp + 4);
;                     const f32x4 na0 = a0 * c0 - b0 * s0, nb0 = a0 * s0 + b0 * c0, na1 = a1 * c1 - b1 * s1, nb1 = a1 * s1 + b1 * c1;
;                     a0 = na0; b0 = nb0; a1 = na1; b1 = nb1; }
;                 a0 = a0 * qs; a1 = a1 * qs; b0 = b0 * qs; b1 = b1 * qs;
;                 bf16_t* rowp = dst + (rowbase + rl) * ld + colh;
;                 *(u32x4*)(rowp) = pack8(a0, a1); *(u32x4*)(rowp + 32) = pack8(b0, b1); }
.LBB0_219:
	s_and_b64 vcc, exec, s[10:11]
	v_add_u32_e32 v32, 0xa0, v158
	s_cbranch_vccnz .LBB0_221
	s_waitcnt vmcnt(2)
	v_mov_b64_e32 v[34:35], v[184:185]
	v_mov_b64_e32 v[36:37], v[186:187]
	v_mov_b64_e32 v[38:39], v[194:195]
	v_mov_b64_e32 v[40:41], v[196:197]
	v_mov_b64_e32 v[42:43], v[230:231]
	v_mov_b64_e32 v[44:45], v[232:233]
	v_mov_b64_e32 v[46:47], v[234:235]
	v_mov_b64_e32 v[48:49], v[236:237]
	s_mov_b64 s[100:101], 0x5800
	v_lshl_add_u64 v[240:241], v[238:239], 0, s[100:101]
	v_lshl_add_u64 v[242:243], v[240:241], 0, s[88:89]
	global_load_dwordx4 v[184:187], v[240:241], off offset:16
	global_load_dwordx4 v[194:197], v[240:241], off
	global_load_dwordx4 v[230:233], v[242:243], off
	global_load_dwordx4 v[234:237], v[242:243], off offset:16
	v_pk_mul_f32 v[50:51], v[22:23], v[44:45]
	v_pk_mul_f32 v[54:55], v[20:21], v[42:43]
	v_pk_fma_f32 v[52:53], v[30:31], v[40:41], v[50:51] neg_lo:[0,0,1] neg_hi:[0,0,1]
	v_pk_fma_f32 v[50:51], v[28:29], v[38:39], v[54:55] neg_lo:[0,0,1] neg_hi:[0,0,1]
	v_pk_mul_f32 v[28:29], v[28:29], v[42:43]
	v_pk_mul_f32 v[30:31], v[30:31], v[44:45]
	v_pk_fma_f32 v[20:21], v[20:21], v[38:39], v[28:29]
	v_pk_mul_f32 v[28:29], v[18:19], v[48:49]
	v_pk_mul_f32 v[38:39], v[16:17], v[46:47]
	v_pk_fma_f32 v[22:23], v[22:23], v[40:41], v[30:31]
	v_pk_fma_f32 v[30:31], v[26:27], v[36:37], v[28:29] neg_lo:[0,0,1] neg_hi:[0,0,1]
	v_pk_fma_f32 v[28:29], v[24:25], v[34:35], v[38:39] neg_lo:[0,0,1] neg_hi:[0,0,1]
	v_pk_mul_f32 v[26:27], v[26:27], v[48:49]
	v_pk_mul_f32 v[24:25], v[24:25], v[46:47]
	v_pk_fma_f32 v[18:19], v[18:19], v[36:37], v[26:27]
	v_pk_fma_f32 v[16:17], v[16:17], v[34:35], v[24:25]
	v_mov_b64_e32 v[24:25], v[28:29]
	v_mov_b64_e32 v[26:27], v[30:31]
	v_mov_b64_e32 v[28:29], v[50:51]
	v_mov_b64_e32 v[30:31], v[52:53]
.LBB0_221:
	v_ashrrev_i32_e32 v33, 31, v32
	s_mov_b32 s58, s54
	s_mov_b32 s59, s54
	v_pk_mul_f32 v[36:37], s[54:55], v[16:17]
	v_lshl_add_u64 v[16:17], s[50:51], 0, v[32:33]
	v_pk_mul_f32 v[30:31], s[58:59], v[30:31]
	v_pk_mul_f32 v[26:27], s[58:59], v[26:27]
	v_pk_mul_f32 v[22:23], s[58:59], v[22:23]
	v_pk_mul_f32 v[34:35], s[58:59], v[18:19]
	v_mad_u64_u32 v[18:19], s[58:59], v16, s52, 0
	v_mov_b32_e32 v16, v19
	v_mad_u64_u32 v[16:17], s[58:59], v17, s52, v[16:17]
	v_pk_mul_f32 v[28:29], s[54:55], v[28:29]
	v_pk_mul_f32 v[24:25], s[54:55], v[24:25]
	v_mov_b32_e32 v19, v16
	v_pk_mul_f32 v[20:21], s[54:55], v[20:21]
	v_lshl_add_u64 v[32:33], v[18:19], 1, v[156:157]
	v_cvt_pk_bf16_f32 v16, v28, v29
	v_cvt_pk_bf16_f32 v17, v30, v31
	v_cvt_pk_bf16_f32 v18, v24, v25
	v_cvt_pk_bf16_f32 v19, v26, v27
	global_store_dwordx4 v[32:33], v[16:19], off
	s_and_b64 vcc, exec, s[8:9]
	s_nop 0
	v_cvt_pk_bf16_f32 v16, v20, v21
	v_cvt_pk_bf16_f32 v17, v22, v23
	v_cvt_pk_bf16_f32 v18, v36, v37
	v_cvt_pk_bf16_f32 v19, v34, v35
	global_store_dwordx4 v[32:33], v[16:19], off offset:64
	s_cbranch_vccnz .LBB0_223
	s_nop 0
	v_pk_mul_f32 v[18:19], v[8:9], v[8:9]
	v_pk_mul_f32 v[16:17], v[10:11], v[10:11]
	v_pk_fma_f32 v[18:19], v[12:13], v[12:13], v[18:19]
	v_pk_fma_f32 v[16:17], v[14:15], v[14:15], v[16:17]
	v_pk_fma_f32 v[18:19], v[4:5], v[4:5], v[18:19]
	v_pk_fma_f32 v[16:17], v[6:7], v[6:7], v[16:17]
	v_pk_fma_f32 v[18:19], v[0:1], v[0:1], v[18:19]
	v_pk_fma_f32 v[16:17], v[2:3], v[2:3], v[16:17]
	v_add_f32_e32 v18, v18, v19
	v_add_f32_e32 v16, v16, v18
	v_cmp_lt_i32_e32 vcc, v206, v204
	v_add_f32_e32 v16, v17, v16
	s_nop 0
	v_cndmask_b32_e32 v17, v203, v206, vcc
	v_lshlrev_b32_e32 v17, 2, v17
	ds_bpermute_b32 v17, v17, v16
	v_cmp_lt_i32_e32 vcc, v205, v204
	s_waitcnt lgkmcnt(0)
	v_add_f32_e32 v16, v16, v17
	v_cndmask_b32_e32 v17, v203, v205, vcc
	v_lshlrev_b32_e32 v17, 2, v17
	ds_bpermute_b32 v17, v17, v16
	s_waitcnt lgkmcnt(0)
	v_add_f32_e32 v16, v16, v17
	v_fmamk_f32 v16, v16, 0x3c800000, v199
	v_mul_f32_e32 v17, 0x4b800000, v16
	v_cmp_gt_f32_e32 vcc, s64, v16
	s_nop 1
	v_cndmask_b32_e32 v16, v16, v17, vcc
	v_rsq_f32_e32 v16, v16
	s_nop 0
	v_mul_f32_e32 v17, 0x45800000, v16
	v_cndmask_b32_e32 v16, v16, v17, vcc
	v_pk_mul_f32 v[12:13], v[12:13], v[16:17] op_sel_hi:[1,0]
	v_pk_mul_f32 v[14:15], v[14:15], v[16:17] op_sel_hi:[1,0]
	v_pk_mul_f32 v[8:9], v[8:9], v[16:17] op_sel_hi:[1,0]
	v_pk_mul_f32 v[10:11], v[10:11], v[16:17] op_sel_hi:[1,0]
	v_pk_mul_f32 v[4:5], v[4:5], v[16:17] op_sel_hi:[1,0]
	v_pk_mul_f32 v[6:7], v[6:7], v[16:17] op_sel_hi:[1,0]
	v_pk_mul_f32 v[0:1], v[0:1], v[16:17] op_sel_hi:[1,0]
	v_pk_mul_f32 v[2:3], v[2:3], v[16:17] op_sel_hi:[1,0]
	s_waitcnt vmcnt(6)
	v_pk_mul_f32 v[14:15], v[78:79], v[14:15]
	v_pk_mul_f32 v[12:13], v[76:77], v[12:13]
	v_pk_mul_f32 v[10:11], v[70:71], v[10:11]
	v_pk_mul_f32 v[8:9], v[68:69], v[8:9]
	v_pk_mul_f32 v[6:7], v[74:75], v[6:7]
	v_pk_mul_f32 v[4:5], v[72:73], v[4:5]
	v_pk_mul_f32 v[2:3], v[66:67], v[2:3]
	v_pk_mul_f32 v[0:1], v[64:65], v[0:1]
.LBB0_223:
	s_mov_b64 s[58:59], 0x300000
	s_and_b64 vcc, exec, s[10:11]
	v_add_u32_e32 v16, 0xb0, v158
	s_cbranch_vccnz .LBB0_225
	s_waitcnt vmcnt(2)
	v_mov_b64_e32 v[18:19], v[184:185]
	v_mov_b64_e32 v[20:21], v[186:187]
	v_mov_b64_e32 v[22:23], v[194:195]
	v_mov_b64_e32 v[24:25], v[196:197]
	v_mov_b64_e32 v[26:27], v[230:231]
	v_mov_b64_e32 v[28:29], v[232:233]
	v_mov_b64_e32 v[30:31], v[234:235]
	v_mov_b64_e32 v[32:33], v[236:237]
	v_pk_mul_f32 v[34:35], v[6:7], v[28:29]
	v_pk_mul_f32 v[38:39], v[4:5], v[26:27]
	v_pk_fma_f32 v[36:37], v[14:15], v[24:25], v[34:35] neg_lo:[0,0,1] neg_hi:[0,0,1]
	v_pk_fma_f32 v[34:35], v[12:13], v[22:23], v[38:39] neg_lo:[0,0,1] neg_hi:[0,0,1]
	v_pk_mul_f32 v[12:13], v[12:13], v[26:27]
	v_pk_mul_f32 v[14:15], v[14:15], v[28:29]
	v_pk_fma_f32 v[4:5], v[4:5], v[22:23], v[12:13]
	v_pk_mul_f32 v[12:13], v[2:3], v[32:33]
	v_pk_mul_f32 v[22:23], v[0:1], v[30:31]
	v_pk_fma_f32 v[6:7], v[6:7], v[24:25], v[14:15]
	v_pk_fma_f32 v[14:15], v[10:11], v[20:21], v[12:13] neg_lo:[0,0,1] neg_hi:[0,0,1]
	v_pk_fma_f32 v[12:13], v[8:9], v[18:19], v[22:23] neg_lo:[0,0,1] neg_hi:[0,0,1]
	v_pk_mul_f32 v[10:11], v[10:11], v[32:33]
	v_pk_mul_f32 v[8:9], v[8:9], v[30:31]
	v_pk_fma_f32 v[2:3], v[2:3], v[20:21], v[10:11]
	v_pk_fma_f32 v[0:1], v[0:1], v[18:19], v[8:9]
	v_mov_b64_e32 v[8:9], v[12:13]
	v_mov_b64_e32 v[10:11], v[14:15]
	v_mov_b64_e32 v[12:13], v[34:35]
	v_mov_b64_e32 v[14:15], v[36:37]

; #define LAS __attribute__((address_space(3)))
; template <int KIND> __global__ void __launch_bounds__(NTHREADS, 2) trunk_fwd(Args args) {
;     extern __shared__ __attribute__((aligned(16))) unsigned char lds_raw[];
;     LAS unsigned char* lds = (LAS unsigned char*)lds_raw;
;     const int G = gridDim.x, ngw = G * NWAVES, ngt = G * NTHREADS;
	.amdhsa_kernel _Z9trunk_fwdILin1EEv4Args
		.amdhsa_group_segment_fixed_size 0
		.amdhsa_private_segment_fixed_size 0
		.amdhsa_kernarg_size 568
		.amdhsa_user_sgpr_count 2
		.amdhsa_user_sgpr_dispatch_ptr 0
		.amdhsa_user_sgpr_queue_ptr 0
		.amdhsa_user_sgpr_kernarg_segment_ptr 1
		.amdhsa_user_sgpr_dispatch_id 0
		.amdhsa_user_sgpr_kernarg_preload_length 0
		.amdhsa_user_sgpr_kernarg_preload_offset 0
		.amdhsa_user_sgpr_private_segment_size 0
		.amdhsa_uses_dynamic_stack 0
		.amdhsa_enable_private_segment 0
		.amdhsa_system_sgpr_workgroup_id_x 1
		.amdhsa_system_sgpr_workgroup_id_y 0
		.amdhsa_system_sgpr_workgroup_id_z 0
		.amdhsa_system_sgpr_workgroup_info 0
		.amdhsa_system_vgpr_workitem_id 2
		.amdhsa_next_free_vgpr 256
		.amdhsa_next_free_sgpr 102
		.amdhsa_accum_offset 256
		.amdhsa_reserve_vcc 1
		.amdhsa_float_round_mode_32 0
		.amdhsa_float_round_mode_16_64 0
		.amdhsa_float_denorm_mode_32 3
		.amdhsa_float_denorm_mode_16_64 3
		.amdhsa_dx10_clamp 1
		.amdhsa_ieee_mode 1
		.amdhsa_fp16_overflow 0
		.amdhsa_tg_split 0
		.amdhsa_exception_fp_ieee_invalid_op 0
		.amdhsa_exception_fp_denorm_src 0
		.amdhsa_exception_fp_ieee_div_zero 0
		.amdhsa_exception_fp_ieee_overflow 0
		.amdhsa_exception_fp_ieee_underflow 0
		.amdhsa_exception_fp_ieee_inexact 0
		.amdhsa_exception_int_div_zero 0
	.end_amdhsa_kernel

; #define LAS __attribute__((address_space(3)))
; template <int KIND> __global__ void __launch_bounds__(NTHREADS, 2) trunk_fwd(Args args) {
;     extern __shared__ __attribute__((aligned(16))) unsigned char lds_raw[];
;     LAS unsigned char* lds = (LAS unsigned char*)lds_raw;
;     const int G = gridDim.x, ngw = G * NWAVES, ngt = G * NTHREADS;
amdhsa.kernels:
  - .agpr_count:     0
    .args:
      - .offset:         0
        .size:           312
        .value_kind:     by_value
      - .offset:         312
        .size:           4
        .value_kind:     hidden_block_count_x
      - .offset:         316
        .size:           4
        .value_kind:     hidden_block_count_y
      - .offset:         320
        .size:           4
        .value_kind:     hidden_block_count_z
      - .offset:         324
        .size:           2
        .value_kind:     hidden_group_size_x
      - .offset:         326
        .size:           2
        .value_kind:     hidden_group_size_y
      - .offset:         328
        .size:           2
        .value_kind:     hidden_group_size_z
      - .offset:         330
        .size:           2
        .value_kind:     hidden_remainder_x
      - .offset:         332
        .size:           2
        .value_kind:     hidden_remainder_y
      - .offset:         334
        .size:           2
        .value_kind:     hidden_remainder_z
      - .offset:         352
        .size:           8
        .value_kind:     hidden_global_offset_x
      - .offset:         360
        .size:           8
        .value_kind:     hidden_global_offset_y
      - .offset:         368
        .size:           8
        .value_kind:     hidden_global_offset_z
      - .offset:         376
        .size:           2
        .value_kind:     hidden_grid_dims
      - .offset:         400
        .size:           8
        .value_kind:     hidden_multigrid_sync_arg
      - .offset:         432
        .size:           4
        .value_kind:     hidden_dynamic_lds_size
    .group_segment_fixed_size: 0
    .kernarg_segment_align: 8
    .kernarg_segment_size: 568
    .language:       OpenCL C
    .language_version:
      - 2
      - 0
    .max_flat_workgroup_size: 512
    .name:           _Z9trunk_fwdILin1EEv4Args
    .private_segment_fixed_size: 0
    .sgpr_count:     108
    .sgpr_spill_count: 78
    .symbol:         _Z9trunk_fwdILin1EEv4Args.kd
    .uniform_work_group_size: 1
    .uses_dynamic_stack: false
    .vgpr_count:     256
    .vgpr_spill_count: 0
    .wavefront_size: 64
